# k46 + POST: removed never-taken denormal rescale around v_rsq (argument >= 1e-6 by construction, 15 sites) and fused square+sum into mul+fmac (14 sites)
# baseline (speedup 1.0000x reference)
; DI unsigned pk2(float lo, float hi) { f32x2 x = {lo, hi}; return __builtin_bit_cast(unsigned, __builtin_convertvector(x, bf16x2_t)); }
; DI float sum32(float v) { v += __shfl_xor(v, 16); return sum16(v); }
; DI f32x2 unpk(unsigned w) { f32x2 r = {bflo(w), bfhi(w)}; return r; }
; DI void post_unit(const Params& p, int l, int unit, LAS unsigned char* lds) {
;     ...
;   for (int tp = 0; tp < 4; ++tp) {
;     constexpr int segcol[16] = {C_QA, C_QA + 128, C_KA, C_QI, C_QI + 128, C_QI + 256, C_QI + 384, C_KI, C_QB, C_QB + 128, C_KB, C_KB + 128, C_QC, C_QC + 128, C_KC, C_KC + 128};
;     unsigned raw2[2][16];
; #pragma unroll
;     for (int hf = 0; hf < 2; ++hf) { const u16* rowl = proj + (tok0 + w * 8 + 2 * tp + hf) * NP;
; #pragma unroll
;       for (int s = 0; s < 16; ++s) raw2[hf][s] = *(const unsigned*)(rowl + segcol[s] + 2 * lane); }
; #pragma unroll
;     for (int hf = 0; hf < 2; ++hf) {
;     const int t = w * 8 + 2 * tp + hf; u16* row = proj + (tok0 + t) * NP;
; #pragma unroll
;     for (int s = 0; s < 16; ++s) {
;       f32x2 x = unpk(raw2[hf][s]); u16* pp = row + segcol[s] + 2 * lane;
;       if (s < 2) {
;         const float rs = rsqrtf(sum32(x[0] * x[0] + x[1] * x[1]) * (1.0f / 64.0f) + EPS);
;         x[0] *= rs * qna[2 * hl]; x[1] *= rs * qna[2 * hl + 1]; rope2<4>(x, hl, cs16 + t * 8);
;         x *= LOG2E * 0.125f; *(unsigned*)pp = pk2(x[0], x[1]);
.LBB0_150:
	ds_read_b128 v[208:211], v35
	ds_read_b128 v[212:215], v35 offset:64
	ds_read_b128 v[216:219], v39
	ds_read_b128 v[220:223], v39 offset:256
	ds_read_b128 v[224:227], v40
	ds_read_b128 v[228:231], v40 offset:32
	ds_read_b128 v[232:235], v35 offset:128
	ds_read_b128 v[236:239], v39 offset:512
	ds_read_b128 v[240:243], v40 offset:64
	s_waitcnt lgkmcnt(0)
	v_lshl_add_u64 v[18:19], v[12:13], 0, v[0:1]
	v_add_co_u32_e32 v20, vcc, 0xa000000, v18
	s_mov_b32 s2, 0xa001000
	s_waitcnt lgkmcnt(0)
	v_addc_co_u32_e32 v21, vcc, 0, v19, vcc
	global_load_dword v49, v[20:21], off
	v_add_co_u32_e32 v22, vcc, s2, v18
	s_mov_b32 s2, 0xa003000
	s_nop 0
	v_addc_co_u32_e32 v23, vcc, 0, v19, vcc
	v_add_co_u32_e32 v42, vcc, s77, v18
	global_load_dword v59, v[20:21], off offset:512
	global_load_dword v70, v[20:21], off offset:768
	global_load_dword v69, v[20:21], off offset:1024
	global_load_dword v68, v[20:21], off offset:1280
	global_load_dword v67, v[20:21], off offset:1536
	global_load_dword v58, v[20:21], off offset:1792
	global_load_dword v71, v[20:21], off offset:256
	v_addc_co_u32_e32 v43, vcc, 0, v19, vcc
	global_load_dword v56, v[20:21], off offset:2432
	global_load_dword v66, v[20:21], off offset:2688
	global_load_dword v65, v[20:21], off offset:2944
	global_load_dword v64, v[20:21], off offset:3200
	global_load_dword v54, v[22:23], off offset:384
	global_load_dword v63, v[22:23], off offset:640
	global_load_dword v62, v[22:23], off offset:896
	global_load_dword v61, v[22:23], off offset:1152
	v_add_co_u32_e32 v20, vcc, s2, v18
	global_load_dword v60, v[42:43], off offset:512
	global_load_dword v57, v[42:43], off offset:768
	global_load_dword v55, v[42:43], off offset:1024
	global_load_dword v53, v[42:43], off offset:1280
	global_load_dword v52, v[42:43], off offset:1536
	global_load_dword v51, v[42:43], off offset:1792
	global_load_dword v50, v[42:43], off offset:2048
	global_load_dword v48, v[42:43], off offset:2304
	v_addc_co_u32_e32 v21, vcc, 0, v19, vcc
	global_load_dword v47, v[42:43], off offset:2944
	global_load_dword v46, v[42:43], off offset:3200
	global_load_dword v45, v[42:43], off offset:3456
	global_load_dword v44, v[42:43], off offset:3712
	s_nop 0
	global_load_dword v43, v[20:21], off offset:896
	global_load_dword v42, v[20:21], off offset:1152
	global_load_dword v41, v[20:21], off offset:1408
	global_load_dword v3, v[20:21], off offset:1664
	s_waitcnt vmcnt(31)
	v_and_b32_e32 v21, 0xffff0000, v49
	v_lshlrev_b32_e32 v20, 16, v49
	v_mul_f32_e32 v22, v20, v20
	v_fmac_f32_e32 v22, v21, v21
	v_mov_b32_e32 v23, v22
	s_nop 1
	v_permlane16_swap_b32_e32 v22, v23
	v_add_f32_e32 v22, v22, v23
	s_nop 1
	v_add_f32_dpp v22, v22, v22 row_ror:8 row_mask:0xf bank_mask:0xf
	s_nop 1
	v_add_f32_dpp v22, v22, v22 row_ror:4 row_mask:0xf bank_mask:0xf
	s_nop 1
	v_add_f32_dpp v22, v22, v22 quad_perm:[2,3,0,1] row_mask:0xf bank_mask:0xf
	s_nop 1
	v_add_f32_dpp v22, v22, v22 quad_perm:[1,0,3,2] row_mask:0xf bank_mask:0xf
	v_fmamk_f32 v22, v22, 0x3c800000, v170
	v_rsq_f32_e32 v22, v22
	s_nop 0
	v_pk_mul_f32 v[22:23], v[4:5], v[22:23] op_sel_hi:[1,0]
	s_nop 0
	v_pk_mul_f32 v[22:23], v[22:23], v[20:21]
	ds_bpermute_b32 v20, v28, v22
	ds_bpermute_b32 v21, v28, v23
	s_and_saveexec_b64 s[2:3], s[12:13]
	s_xor_b64 s[18:19], exec, s[2:3]
	s_cbranch_execz .LBB0_154
	s_and_saveexec_b64 s[30:31], s[14:15]
	s_cbranch_execz .LBB0_153
	v_add_u32_e32 v49, 0, v35
	s_waitcnt lgkmcnt(0)
	v_mul_f32_e32 v22, v22, v208
	v_mul_f32_e32 v23, v23, v210
	v_fmac_f32_e32 v22, v209, v20
	v_fmac_f32_e32 v23, v21, v211

; DI unsigned pk2(float lo, float hi) { f32x2 x = {lo, hi}; return __builtin_bit_cast(unsigned, __builtin_convertvector(x, bf16x2_t)); }
; DI float sum32(float v) { v += __shfl_xor(v, 16); return sum16(v); }
; DI f32x2 unpk(unsigned w) { f32x2 r = {bflo(w), bfhi(w)}; return r; }
; DI void post_unit(const Params& p, int l, int unit, LAS unsigned char* lds) {
;     ...
;     for (int s = 0; s < 16; ++s) {
;       f32x2 x = unpk(raw2[hf][s]); u16* pp = row + segcol[s] + 2 * lane;
;       if (s < 2) {
;         const float rs = rsqrtf(sum32(x[0] * x[0] + x[1] * x[1]) * (1.0f / 64.0f) + EPS);
;         x[0] *= rs * qna[2 * hl]; x[1] *= rs * qna[2 * hl + 1]; rope2<4>(x, hl, cs16 + t * 8);
;         x *= LOG2E * 0.125f; *(unsigned*)pp = pk2(x[0], x[1]);
.LBB0_156:
	s_or_b64 exec, exec, s[18:19]
	s_mov_b64 s[2:3], 0xa000000
	s_waitcnt lgkmcnt(0)
	v_lshl_add_u64 v[20:21], v[18:19], 0, s[2:3]
	s_mov_b32 s2, 0x3e38aa3b
	v_pk_mul_f32 v[22:23], v[22:23], s[2:3] op_sel_hi:[1,0]
	s_nop 0
	v_cvt_pk_bf16_f32 v22, v22, v23
	global_store_dword v[20:21], v22, off
	s_waitcnt vmcnt(25)
	v_and_b32_e32 v21, 0xffff0000, v71
	v_lshlrev_b32_e32 v20, 16, v71
	v_mul_f32_e32 v22, v20, v20
	v_fmac_f32_e32 v22, v21, v21
	v_mov_b32_e32 v23, v22
	s_nop 1
	v_permlane16_swap_b32_e32 v22, v23
	v_add_f32_e32 v22, v22, v23
	s_nop 1
	v_add_f32_dpp v22, v22, v22 row_ror:8 row_mask:0xf bank_mask:0xf
	s_nop 1
	v_add_f32_dpp v22, v22, v22 row_ror:4 row_mask:0xf bank_mask:0xf
	s_nop 1
	v_add_f32_dpp v22, v22, v22 quad_perm:[2,3,0,1] row_mask:0xf bank_mask:0xf
	s_nop 1
	v_add_f32_dpp v22, v22, v22 quad_perm:[1,0,3,2] row_mask:0xf bank_mask:0xf
	v_fmamk_f32 v22, v22, 0x3c800000, v170
	v_rsq_f32_e32 v22, v22
	s_nop 0
	v_pk_mul_f32 v[22:23], v[4:5], v[22:23] op_sel_hi:[1,0]
	s_nop 0
	v_pk_mul_f32 v[22:23], v[22:23], v[20:21]
	ds_bpermute_b32 v20, v28, v22
	ds_bpermute_b32 v21, v28, v23
	s_and_saveexec_b64 s[2:3], s[12:13]
	s_xor_b64 s[18:19], exec, s[2:3]
	s_cbranch_execz .LBB0_160
	s_and_saveexec_b64 s[30:31], s[14:15]
	s_cbranch_execz .LBB0_159
	s_waitcnt lgkmcnt(0)
	v_mul_f32_e32 v22, v22, v208
	v_mul_f32_e32 v23, v23, v210
	v_fmac_f32_e32 v22, v209, v20
	v_fmac_f32_e32 v23, v21, v211

; #define LAS __attribute__((address_space(3)))
; DI unsigned pk2(float lo, float hi) { f32x2 x = {lo, hi}; return __builtin_bit_cast(unsigned, __builtin_convertvector(x, bf16x2_t)); }
; DI float sum32(float v) { v += __shfl_xor(v, 16); return sum16(v); }
; DI float sum64(float v) { v += __shfl_xor(v, 32); return sum32(v); }
; DI f32x2 unpk(unsigned w) { f32x2 r = {bflo(w), bfhi(w)}; return r; }
; DI void post_unit(const Params& p, int l, int unit, LAS unsigned char* lds) {
;     ...
;     for (int s = 0; s < 16; ++s) {
;       f32x2 x = unpk(raw2[hf][s]); u16* pp = row + segcol[s] + 2 * lane;
;       if (s < 2) {
;         const float rs = rsqrtf(sum32(x[0] * x[0] + x[1] * x[1]) * (1.0f / 64.0f) + EPS);
;         x[0] *= rs * qna[2 * hl]; x[1] *= rs * qna[2 * hl + 1]; rope2<4>(x, hl, cs16 + t * 8);
;         x *= LOG2E * 0.125f; *(unsigned*)pp = pk2(x[0], x[1]);
;       } else if (s == 2) {
;         const float rs = rsqrtf(sum64(x[0] * x[0] + x[1] * x[1]) * (1.0f / 128.0f) + EPS);
;         *(LAS unsigned*)(At + t * 272 + lane * 4) = pk2(x[0] * rs, x[1] * rs);
;       } else if (s < 7) {
;         rope2<4>(x, hl, cs16 + t * 8); *(unsigned*)pp = pk2(x[0], x[1]);
.LBB0_162:
	s_or_b64 exec, exec, s[18:19]
	s_mov_b64 s[2:3], 0xa000100
	s_waitcnt lgkmcnt(0)
	v_lshl_add_u64 v[20:21], v[18:19], 0, s[2:3]
	s_mov_b32 s2, 0x3e38aa3b
	v_pk_mul_f32 v[22:23], v[22:23], s[2:3] op_sel_hi:[1,0]
	s_nop 0
	v_cvt_pk_bf16_f32 v22, v22, v23
	global_store_dword v[20:21], v22, off
	v_lshlrev_b32_e32 v20, 16, v59
	v_and_b32_e32 v21, 0xffff0000, v59
	v_pk_mul_f32 v[22:23], v[20:21], v[20:21]
	v_add_u32_e32 v59, 0, v33
	v_add_f32_e32 v22, v22, v23
	v_mov_b32_e32 v23, v22
	s_nop 1
	v_permlane32_swap_b32_e32 v22, v23
	v_add_f32_e32 v22, v22, v23
	v_mov_b32_e32 v23, v22
	s_nop 1
	v_permlane16_swap_b32_e32 v22, v23
	v_add_f32_e32 v22, v22, v23
	s_nop 1
	v_add_f32_dpp v22, v22, v22 row_ror:8 row_mask:0xf bank_mask:0xf
	s_nop 1
	v_add_f32_dpp v22, v22, v22 row_ror:4 row_mask:0xf bank_mask:0xf
	s_nop 1
	v_add_f32_dpp v22, v22, v22 quad_perm:[2,3,0,1] row_mask:0xf bank_mask:0xf
	s_nop 1
	v_add_f32_dpp v22, v22, v22 quad_perm:[1,0,3,2] row_mask:0xf bank_mask:0xf
	v_fmamk_f32 v22, v22, 0x3c000000, v170
	v_rsq_f32_e32 v22, v22
	s_nop 0
	v_pk_mul_f32 v[20:21], v[22:23], v[20:21] op_sel_hi:[0,1]
	v_cvt_pk_bf16_f32 v20, v20, v21
	ds_write_b32 v59, v20
	v_lshlrev_b32_e32 v20, 16, v70
	v_and_b32_e32 v21, 0xffff0000, v70
	ds_bpermute_b32 v70, v28, v20
	ds_bpermute_b32 v23, v28, v21
	s_and_saveexec_b64 s[2:3], s[12:13]
	s_xor_b64 s[18:19], exec, s[2:3]
	s_cbranch_execz .LBB0_166
	s_and_saveexec_b64 s[30:31], s[14:15]
	s_cbranch_execz .LBB0_165
	v_mov_b32_e32 v22, v21
	s_waitcnt lgkmcnt(0)
	v_mul_f32_e32 v20, v208, v20
	v_mul_f32_e32 v21, v210, v22
	v_fmac_f32_e32 v20, v209, v70
	v_fmac_f32_e32 v21, v211, v23

; DI unsigned pk2(float lo, float hi) { f32x2 x = {lo, hi}; return __builtin_bit_cast(unsigned, __builtin_convertvector(x, bf16x2_t)); }
; DI float sum32(float v) { v += __shfl_xor(v, 16); return sum16(v); }
; DI void post_unit(const Params& p, int l, int unit, LAS unsigned char* lds) {
;     ...
;       } else if (s < 7) {
;         rope2<4>(x, hl, cs16 + t * 8); *(unsigned*)pp = pk2(x[0], x[1]);
;       } else if (s == 7) {
;         const float rs = rsqrtf(sum32(x[0] * x[0] + x[1] * x[1]) * (1.0f / 64.0f) + EPS);
;         x *= rs; rope2<4>(x, hl, cs16 + t * 8); if (lane < 32) *(unsigned*)((u16*)(p.ws + WS_KIC) + (tok0 + t) * 64 + 2 * lane) = pk2(x[0], x[1]);
.LBB0_186:
	s_or_b64 exec, exec, s[18:19]
	s_mov_b64 s[2:3], 0xa000600
	s_waitcnt lgkmcnt(0)
	v_lshl_add_u64 v[22:23], v[18:19], 0, s[2:3]
	v_cvt_pk_bf16_f32 v20, v20, v21
	global_store_dword v[22:23], v20, off
	v_lshlrev_b32_e32 v20, 16, v58
	v_and_b32_e32 v21, 0xffff0000, v58
	v_mul_f32_e32 v22, v20, v20
	v_fmac_f32_e32 v22, v21, v21
	v_mov_b32_e32 v23, v22
	s_nop 1
	v_permlane16_swap_b32_e32 v22, v23
	v_add_f32_e32 v22, v22, v23
	s_nop 1
	v_add_f32_dpp v22, v22, v22 row_ror:8 row_mask:0xf bank_mask:0xf
	s_nop 1
	v_add_f32_dpp v22, v22, v22 row_ror:4 row_mask:0xf bank_mask:0xf
	s_nop 1
	v_add_f32_dpp v22, v22, v22 quad_perm:[2,3,0,1] row_mask:0xf bank_mask:0xf
	s_nop 1
	v_add_f32_dpp v22, v22, v22 quad_perm:[1,0,3,2] row_mask:0xf bank_mask:0xf
	v_fmamk_f32 v22, v22, 0x3c800000, v170
	v_rsq_f32_e32 v22, v22
	s_nop 0
	v_pk_mul_f32 v[20:21], v[22:23], v[20:21] op_sel_hi:[0,1]
	ds_bpermute_b32 v22, v28, v20
	ds_bpermute_b32 v23, v28, v21
	s_and_saveexec_b64 s[2:3], s[12:13]
	s_xor_b64 s[18:19], exec, s[2:3]
	s_cbranch_execz .LBB0_314
	s_and_saveexec_b64 s[30:31], s[14:15]
	s_cbranch_execz .LBB0_189
	s_waitcnt lgkmcnt(0)
	v_mul_f32_e32 v20, v20, v208
	v_mul_f32_e32 v21, v210, v21
	v_fmac_f32_e32 v20, v209, v22
	v_fmac_f32_e32 v21, v211, v23

; DI unsigned pk2(float lo, float hi) { f32x2 x = {lo, hi}; return __builtin_bit_cast(unsigned, __builtin_convertvector(x, bf16x2_t)); }
; DI float sum16(float v) { v += __shfl_xor(v, 8); v += __shfl_xor(v, 4); v += __shfl_xor(v, 2); v += __shfl_xor(v, 1); return v; }
; DI void post_unit(const Params& p, int l, int unit, LAS unsigned char* lds) {
;     ...
;       } else if (s < 12) {
;         rope2<16>(x, hl, cs64 + t * 32);
;         const int hd = ((s & 1) ? 2 : 0) + hsel;
;         const float lg = log1pf(-exp2f(-5.0f - (float)hd));
;         const float f = (s < 10) ? expf(lg * (float)(t + 1)) : expf(lg * (float)(63 - t)) * 0.125f;
;         x *= f; *(unsigned*)pp = pk2(x[0], x[1]);
;       } else {
;         const float* gn = (s < 14) ? qnc : knc;
;         const float rs = rsqrtf(sum16(x[0] * x[0] + x[1] * x[1]) * (1.0f / 32.0f) + EPS);
;         x[0] *= rs * gn[2 * hl16]; x[1] *= rs * gn[2 * hl16 + 1]; rope2<2>(x, hl16, cs8 + t * 4);
;         if (s < 14) x *= LOG2E * 0.17677669529663687f;
;         *(unsigned*)pp = pk2(x[0], x[1]);
.LBB0_208:
	s_or_b64 exec, exec, s[18:19]
	s_waitcnt lgkmcnt(1)
	v_mul_f32_e32 v64, v32, v65
	v_mul_f32_e32 v65, 0x3fb8aa3b, v64
	v_fma_f32 v66, v64, s64, -v65
	v_rndne_f32_e32 v67, v65
	v_fmac_f32_e32 v66, 0x32a5705f, v64
	v_sub_f32_e32 v65, v65, v67
	v_add_f32_e32 v65, v65, v66
	v_exp_f32_e32 v65, v65
	v_cvt_i32_f32_e32 v66, v67
	v_cmp_ngt_f32_e32 vcc, s65, v64
	s_mov_b64 s[2:3], 0xa000c80
	s_waitcnt lgkmcnt(0)
	v_lshl_add_u64 v[20:21], v[18:19], 0, s[2:3]
	v_ldexp_f32 v65, v65, v66
	v_cndmask_b32_e32 v65, 0, v65, vcc
	v_cmp_nlt_f32_e32 vcc, s89, v64
	s_nop 1
	v_cndmask_b32_e32 v64, v177, v65, vcc
	v_mul_f32_e32 v64, 0x3e000000, v64
	v_pk_mul_f32 v[22:23], v[64:65], v[22:23] op_sel_hi:[0,1]
	v_cvt_pk_bf16_f32 v22, v22, v23
	global_store_dword v[20:21], v22, off
	s_waitcnt vmcnt(29)
	v_lshlrev_b32_e32 v20, 16, v54
	v_and_b32_e32 v21, 0xffff0000, v54
	v_mul_f32_e32 v22, v20, v20
	v_fmac_f32_e32 v22, v21, v21
	s_nop 1
	v_add_f32_dpp v22, v22, v22 row_ror:8 row_mask:0xf bank_mask:0xf
	s_nop 1
	v_add_f32_dpp v22, v22, v22 row_ror:4 row_mask:0xf bank_mask:0xf
	s_nop 1
	v_add_f32_dpp v22, v22, v22 quad_perm:[2,3,0,1] row_mask:0xf bank_mask:0xf
	s_nop 1
	v_add_f32_dpp v22, v22, v22 quad_perm:[1,0,3,2] row_mask:0xf bank_mask:0xf
	v_fmamk_f32 v22, v22, 0x3d000000, v170
	v_rsq_f32_e32 v22, v22
	s_nop 0
	v_pk_mul_f32 v[22:23], v[6:7], v[22:23] op_sel_hi:[1,0]
	s_nop 0
	v_pk_mul_f32 v[22:23], v[22:23], v[20:21]
	ds_bpermute_b32 v20, v29, v22
	ds_bpermute_b32 v21, v29, v23
	s_and_saveexec_b64 s[2:3], s[6:7]
	s_xor_b64 s[18:19], exec, s[2:3]
	s_cbranch_execz .LBB0_212
	s_and_saveexec_b64 s[30:31], s[8:9]
	s_cbranch_execz .LBB0_211
	v_add_u32_e32 v54, 0, v40
	s_waitcnt lgkmcnt(0)
	v_mul_f32_e32 v22, v22, v224
	v_mul_f32_e32 v23, v23, v226
	v_fmac_f32_e32 v22, v225, v20
	v_fmac_f32_e32 v23, v21, v227

; DI unsigned pk2(float lo, float hi) { f32x2 x = {lo, hi}; return __builtin_bit_cast(unsigned, __builtin_convertvector(x, bf16x2_t)); }
; DI float sum16(float v) { v += __shfl_xor(v, 8); v += __shfl_xor(v, 4); v += __shfl_xor(v, 2); v += __shfl_xor(v, 1); return v; }
; DI void post_unit(const Params& p, int l, int unit, LAS unsigned char* lds) {
;     ...
;       } else {
;         const float* gn = (s < 14) ? qnc : knc;
;         const float rs = rsqrtf(sum16(x[0] * x[0] + x[1] * x[1]) * (1.0f / 32.0f) + EPS);
;         x[0] *= rs * gn[2 * hl16]; x[1] *= rs * gn[2 * hl16 + 1]; rope2<2>(x, hl16, cs8 + t * 4);
;         if (s < 14) x *= LOG2E * 0.17677669529663687f;
;         *(unsigned*)pp = pk2(x[0], x[1]);
.LBB0_214:
	s_or_b64 exec, exec, s[18:19]
	s_mov_b64 s[2:3], 0xa001180
	s_waitcnt lgkmcnt(0)
	v_lshl_add_u64 v[20:21], v[18:19], 0, s[2:3]
	s_mov_b32 s2, 0x3e8293ee
	v_pk_mul_f32 v[22:23], v[22:23], s[2:3] op_sel_hi:[1,0]
	s_nop 0
	v_cvt_pk_bf16_f32 v22, v22, v23
	global_store_dword v[20:21], v22, off
	s_waitcnt vmcnt(29)
	v_lshlrev_b32_e32 v20, 16, v63
	v_and_b32_e32 v21, 0xffff0000, v63
	v_mul_f32_e32 v22, v20, v20
	v_fmac_f32_e32 v22, v21, v21
	s_nop 1
	v_add_f32_dpp v22, v22, v22 row_ror:8 row_mask:0xf bank_mask:0xf
	s_nop 1
	v_add_f32_dpp v22, v22, v22 row_ror:4 row_mask:0xf bank_mask:0xf
	s_nop 1
	v_add_f32_dpp v22, v22, v22 quad_perm:[2,3,0,1] row_mask:0xf bank_mask:0xf
	s_nop 1
	v_add_f32_dpp v22, v22, v22 quad_perm:[1,0,3,2] row_mask:0xf bank_mask:0xf
	v_fmamk_f32 v22, v22, 0x3d000000, v170
	v_rsq_f32_e32 v22, v22
	s_nop 0
	v_pk_mul_f32 v[22:23], v[6:7], v[22:23] op_sel_hi:[1,0]
	s_nop 0
	v_pk_mul_f32 v[22:23], v[22:23], v[20:21]
	ds_bpermute_b32 v20, v29, v22
	ds_bpermute_b32 v21, v29, v23
	s_and_saveexec_b64 s[2:3], s[6:7]
	s_xor_b64 s[18:19], exec, s[2:3]
	s_cbranch_execz .LBB0_218
	s_and_saveexec_b64 s[30:31], s[8:9]
	s_cbranch_execz .LBB0_217
	s_waitcnt lgkmcnt(0)
	v_mul_f32_e32 v22, v22, v224
	v_mul_f32_e32 v23, v23, v226
	v_fmac_f32_e32 v22, v225, v20
	v_fmac_f32_e32 v23, v21, v227

; DI unsigned pk2(float lo, float hi) { f32x2 x = {lo, hi}; return __builtin_bit_cast(unsigned, __builtin_convertvector(x, bf16x2_t)); }
; DI float sum16(float v) { v += __shfl_xor(v, 8); v += __shfl_xor(v, 4); v += __shfl_xor(v, 2); v += __shfl_xor(v, 1); return v; }
; DI void post_unit(const Params& p, int l, int unit, LAS unsigned char* lds) {
;     ...
;       } else {
;         const float* gn = (s < 14) ? qnc : knc;
;         const float rs = rsqrtf(sum16(x[0] * x[0] + x[1] * x[1]) * (1.0f / 32.0f) + EPS);
;         x[0] *= rs * gn[2 * hl16]; x[1] *= rs * gn[2 * hl16 + 1]; rope2<2>(x, hl16, cs8 + t * 4);
;         if (s < 14) x *= LOG2E * 0.17677669529663687f;
;         *(unsigned*)pp = pk2(x[0], x[1]);
.LBB0_220:
	s_or_b64 exec, exec, s[18:19]
	s_mov_b64 s[2:3], 0xa001280
	s_waitcnt lgkmcnt(0)
	v_lshl_add_u64 v[20:21], v[18:19], 0, s[2:3]
	s_mov_b32 s2, 0x3e8293ee
	v_pk_mul_f32 v[22:23], v[22:23], s[2:3] op_sel_hi:[1,0]
	s_nop 0
	v_cvt_pk_bf16_f32 v22, v22, v23
	global_store_dword v[20:21], v22, off
	s_waitcnt vmcnt(29)
	v_lshlrev_b32_e32 v20, 16, v62
	v_and_b32_e32 v21, 0xffff0000, v62
	v_mul_f32_e32 v22, v20, v20
	v_fmac_f32_e32 v22, v21, v21
	s_nop 1
	v_add_f32_dpp v22, v22, v22 row_ror:8 row_mask:0xf bank_mask:0xf
	s_nop 1
	v_add_f32_dpp v22, v22, v22 row_ror:4 row_mask:0xf bank_mask:0xf
	s_nop 1
	v_add_f32_dpp v22, v22, v22 quad_perm:[2,3,0,1] row_mask:0xf bank_mask:0xf
	s_nop 1
	v_add_f32_dpp v22, v22, v22 quad_perm:[1,0,3,2] row_mask:0xf bank_mask:0xf
	v_fmamk_f32 v22, v22, 0x3d000000, v170
	v_rsq_f32_e32 v22, v22
	s_nop 0
	v_pk_mul_f32 v[22:23], v[8:9], v[22:23] op_sel_hi:[1,0]
	s_nop 0
	v_pk_mul_f32 v[22:23], v[22:23], v[20:21]
	ds_bpermute_b32 v20, v29, v22
	ds_bpermute_b32 v21, v29, v23
	s_and_saveexec_b64 s[2:3], s[6:7]
	s_xor_b64 s[18:19], exec, s[2:3]
	s_cbranch_execz .LBB0_224
	s_and_saveexec_b64 s[30:31], s[8:9]
	s_cbranch_execz .LBB0_223
	s_waitcnt lgkmcnt(0)
	v_mul_f32_e32 v22, v22, v224
	v_mul_f32_e32 v23, v23, v226
	v_fmac_f32_e32 v22, v225, v20
	v_fmac_f32_e32 v23, v21, v227

; DI unsigned pk2(float lo, float hi) { f32x2 x = {lo, hi}; return __builtin_bit_cast(unsigned, __builtin_convertvector(x, bf16x2_t)); }
; DI float sum16(float v) { v += __shfl_xor(v, 8); v += __shfl_xor(v, 4); v += __shfl_xor(v, 2); v += __shfl_xor(v, 1); return v; }
; DI void post_unit(const Params& p, int l, int unit, LAS unsigned char* lds) {
;     ...
;       } else {
;         const float* gn = (s < 14) ? qnc : knc;
;         const float rs = rsqrtf(sum16(x[0] * x[0] + x[1] * x[1]) * (1.0f / 32.0f) + EPS);
;         x[0] *= rs * gn[2 * hl16]; x[1] *= rs * gn[2 * hl16 + 1]; rope2<2>(x, hl16, cs8 + t * 4);
;         if (s < 14) x *= LOG2E * 0.17677669529663687f;
;         *(unsigned*)pp = pk2(x[0], x[1]);
.LBB0_226:
	s_or_b64 exec, exec, s[18:19]
	s_mov_b64 s[2:3], 0xa001380
	s_waitcnt lgkmcnt(0)
	v_lshl_add_u64 v[20:21], v[18:19], 0, s[2:3]
	v_cvt_pk_bf16_f32 v22, v22, v23
	global_store_dword v[20:21], v22, off
	s_waitcnt vmcnt(29)
	v_lshlrev_b32_e32 v20, 16, v61
	v_and_b32_e32 v21, 0xffff0000, v61
	v_mul_f32_e32 v22, v20, v20
	v_fmac_f32_e32 v22, v21, v21
	s_nop 1
	v_add_f32_dpp v22, v22, v22 row_ror:8 row_mask:0xf bank_mask:0xf
	s_nop 1
	v_add_f32_dpp v22, v22, v22 row_ror:4 row_mask:0xf bank_mask:0xf
	s_nop 1
	v_add_f32_dpp v22, v22, v22 quad_perm:[2,3,0,1] row_mask:0xf bank_mask:0xf
	s_nop 1
	v_add_f32_dpp v22, v22, v22 quad_perm:[1,0,3,2] row_mask:0xf bank_mask:0xf
	v_fmamk_f32 v22, v22, 0x3d000000, v170
	v_rsq_f32_e32 v22, v22
	s_nop 0
	v_pk_mul_f32 v[22:23], v[8:9], v[22:23] op_sel_hi:[1,0]
	s_nop 0
	v_pk_mul_f32 v[22:23], v[22:23], v[20:21]
	ds_bpermute_b32 v20, v29, v22
	ds_bpermute_b32 v21, v29, v23
	s_and_saveexec_b64 s[2:3], s[6:7]
	s_xor_b64 s[18:19], exec, s[2:3]
	s_cbranch_execz .LBB0_230
	s_and_saveexec_b64 s[30:31], s[8:9]
	s_cbranch_execz .LBB0_229
	s_waitcnt lgkmcnt(0)
	v_mul_f32_e32 v22, v22, v224
	v_mul_f32_e32 v23, v23, v226
	v_fmac_f32_e32 v22, v225, v20
	v_fmac_f32_e32 v23, v21, v227

; DI unsigned pk2(float lo, float hi) { f32x2 x = {lo, hi}; return __builtin_bit_cast(unsigned, __builtin_convertvector(x, bf16x2_t)); }
; DI float sum32(float v) { v += __shfl_xor(v, 16); return sum16(v); }
; DI f32x2 unpk(unsigned w) { f32x2 r = {bflo(w), bfhi(w)}; return r; }
; DI void post_unit(const Params& p, int l, int unit, LAS unsigned char* lds) {
;     ...
;     for (int s = 0; s < 16; ++s) {
;       f32x2 x = unpk(raw2[hf][s]); u16* pp = row + segcol[s] + 2 * lane;
;       if (s < 2) {
;         const float rs = rsqrtf(sum32(x[0] * x[0] + x[1] * x[1]) * (1.0f / 64.0f) + EPS);
;         x[0] *= rs * qna[2 * hl]; x[1] *= rs * qna[2 * hl + 1]; rope2<4>(x, hl, cs16 + t * 8);
;         x *= LOG2E * 0.125f; *(unsigned*)pp = pk2(x[0], x[1]);
.LBB0_232:
	s_or_b64 exec, exec, s[18:19]
	s_mov_b64 s[2:3], 0xa001480
	v_lshl_add_u64 v[18:19], v[18:19], 0, s[2:3]
	s_waitcnt lgkmcnt(1)
	v_cvt_pk_bf16_f32 v20, v22, v23
	global_store_dword v[18:19], v20, off
	s_waitcnt vmcnt(29)
	v_and_b32_e32 v19, 0xffff0000, v60
	v_lshlrev_b32_e32 v18, 16, v60
	s_waitcnt lgkmcnt(0)
	v_mul_f32_e32 v20, v18, v18
	v_fmac_f32_e32 v20, v19, v19
	v_mov_b32_e32 v21, v20
	s_nop 1
	v_permlane16_swap_b32_e32 v20, v21
	v_add_f32_e32 v20, v20, v21
	s_nop 1
	v_add_f32_dpp v20, v20, v20 row_ror:8 row_mask:0xf bank_mask:0xf
	s_nop 1
	v_add_f32_dpp v20, v20, v20 row_ror:4 row_mask:0xf bank_mask:0xf
	s_nop 1
	v_add_f32_dpp v20, v20, v20 quad_perm:[2,3,0,1] row_mask:0xf bank_mask:0xf
	s_nop 1
	v_add_f32_dpp v20, v20, v20 quad_perm:[1,0,3,2] row_mask:0xf bank_mask:0xf
	v_fmamk_f32 v20, v20, 0x3c800000, v170
	v_rsq_f32_e32 v20, v20
	s_nop 0
	v_pk_mul_f32 v[20:21], v[4:5], v[20:21] op_sel_hi:[1,0]
	s_nop 0
	v_pk_mul_f32 v[20:21], v[20:21], v[18:19]
	ds_bpermute_b32 v18, v28, v20
	ds_bpermute_b32 v19, v28, v21
	s_and_saveexec_b64 s[2:3], s[12:13]
	s_xor_b64 s[18:19], exec, s[2:3]
	s_cbranch_execz .LBB0_236
	s_and_saveexec_b64 s[30:31], s[14:15]
	s_cbranch_execz .LBB0_235
	s_waitcnt lgkmcnt(0)
	v_mul_f32_e32 v20, v20, v212
	v_mul_f32_e32 v21, v21, v214
	v_fmac_f32_e32 v20, v213, v18
	v_fmac_f32_e32 v21, v19, v215

; DI unsigned pk2(float lo, float hi) { f32x2 x = {lo, hi}; return __builtin_bit_cast(unsigned, __builtin_convertvector(x, bf16x2_t)); }
; DI float sum32(float v) { v += __shfl_xor(v, 16); return sum16(v); }
; DI f32x2 unpk(unsigned w) { f32x2 r = {bflo(w), bfhi(w)}; return r; }
; DI void post_unit(const Params& p, int l, int unit, LAS unsigned char* lds) {
;     ...
;     for (int s = 0; s < 16; ++s) {
;       f32x2 x = unpk(raw2[hf][s]); u16* pp = row + segcol[s] + 2 * lane;
;       if (s < 2) {
;         const float rs = rsqrtf(sum32(x[0] * x[0] + x[1] * x[1]) * (1.0f / 64.0f) + EPS);
;         x[0] *= rs * qna[2 * hl]; x[1] *= rs * qna[2 * hl + 1]; rope2<4>(x, hl, cs16 + t * 8);
;         x *= LOG2E * 0.125f; *(unsigned*)pp = pk2(x[0], x[1]);
.LBB0_238:
	s_or_b64 exec, exec, s[18:19]
	s_mov_b32 s2, 0x3e38aa3b
	s_waitcnt lgkmcnt(0)
	v_lshl_add_u64 v[18:19], v[14:15], 0, v[0:1]
	v_pk_mul_f32 v[20:21], v[20:21], s[2:3] op_sel_hi:[1,0]
	s_nop 0
	v_cvt_pk_bf16_f32 v22, v20, v21
	v_add_co_u32_e32 v20, vcc, 0xa002000, v18
	s_nop 1
	v_addc_co_u32_e32 v21, vcc, 0, v19, vcc
	global_store_dword v[20:21], v22, off offset:512
	s_waitcnt vmcnt(29)
	v_and_b32_e32 v21, 0xffff0000, v57
	v_lshlrev_b32_e32 v20, 16, v57
	v_mul_f32_e32 v22, v20, v20
	v_fmac_f32_e32 v22, v21, v21
	v_mov_b32_e32 v23, v22
	s_nop 1
	v_permlane16_swap_b32_e32 v22, v23
	v_add_f32_e32 v22, v22, v23
	s_nop 1
	v_add_f32_dpp v22, v22, v22 row_ror:8 row_mask:0xf bank_mask:0xf
	s_nop 1
	v_add_f32_dpp v22, v22, v22 row_ror:4 row_mask:0xf bank_mask:0xf
	s_nop 1
	v_add_f32_dpp v22, v22, v22 quad_perm:[2,3,0,1] row_mask:0xf bank_mask:0xf
	s_nop 1
	v_add_f32_dpp v22, v22, v22 quad_perm:[1,0,3,2] row_mask:0xf bank_mask:0xf
	v_fmamk_f32 v22, v22, 0x3c800000, v170
	v_rsq_f32_e32 v22, v22
	s_nop 0
	v_pk_mul_f32 v[22:23], v[4:5], v[22:23] op_sel_hi:[1,0]
	s_nop 0
	v_pk_mul_f32 v[22:23], v[22:23], v[20:21]
	ds_bpermute_b32 v20, v28, v22
	ds_bpermute_b32 v21, v28, v23
	s_and_saveexec_b64 s[2:3], s[12:13]
	s_xor_b64 s[18:19], exec, s[2:3]
	s_cbranch_execz .LBB0_242
	s_and_saveexec_b64 s[30:31], s[14:15]
	s_cbranch_execz .LBB0_241
	s_waitcnt lgkmcnt(0)
	v_mul_f32_e32 v22, v22, v212
	v_mul_f32_e32 v23, v23, v214
	v_fmac_f32_e32 v22, v213, v20
	v_fmac_f32_e32 v23, v21, v215

; #define LAS __attribute__((address_space(3)))
; DI unsigned pk2(float lo, float hi) { f32x2 x = {lo, hi}; return __builtin_bit_cast(unsigned, __builtin_convertvector(x, bf16x2_t)); }
; DI float sum32(float v) { v += __shfl_xor(v, 16); return sum16(v); }
; DI float sum64(float v) { v += __shfl_xor(v, 32); return sum32(v); }
; DI f32x2 unpk(unsigned w) { f32x2 r = {bflo(w), bfhi(w)}; return r; }
; DI void post_unit(const Params& p, int l, int unit, LAS unsigned char* lds) {
;     ...
;     for (int s = 0; s < 16; ++s) {
;       f32x2 x = unpk(raw2[hf][s]); u16* pp = row + segcol[s] + 2 * lane;
;       if (s < 2) {
;         const float rs = rsqrtf(sum32(x[0] * x[0] + x[1] * x[1]) * (1.0f / 64.0f) + EPS);
;         x[0] *= rs * qna[2 * hl]; x[1] *= rs * qna[2 * hl + 1]; rope2<4>(x, hl, cs16 + t * 8);
;         x *= LOG2E * 0.125f; *(unsigned*)pp = pk2(x[0], x[1]);
;       } else if (s == 2) {
;         const float rs = rsqrtf(sum64(x[0] * x[0] + x[1] * x[1]) * (1.0f / 128.0f) + EPS);
;         *(LAS unsigned*)(At + t * 272 + lane * 4) = pk2(x[0] * rs, x[1] * rs);
;       } else if (s < 7) {
;         rope2<4>(x, hl, cs16 + t * 8); *(unsigned*)pp = pk2(x[0], x[1]);
.LBB0_244:
	s_or_b64 exec, exec, s[18:19]
	s_mov_b32 s2, 0x3e38aa3b
	s_waitcnt lgkmcnt(0)
	v_pk_mul_f32 v[20:21], v[22:23], s[2:3] op_sel_hi:[1,0]
	s_nop 0
	v_cvt_pk_bf16_f32 v22, v20, v21
	v_add_co_u32_e32 v20, vcc, 0xa002000, v18
	s_nop 1
	v_addc_co_u32_e32 v21, vcc, 0, v19, vcc
	global_store_dword v[20:21], v22, off offset:768
	s_waitcnt vmcnt(29)
	v_lshlrev_b32_e32 v20, 16, v55
	v_and_b32_e32 v21, 0xffff0000, v55
	v_mul_f32_e32 v22, v20, v20
	v_fmac_f32_e32 v22, v21, v21
	v_mov_b32_e32 v23, v22
	s_nop 1
	v_permlane32_swap_b32_e32 v22, v23
	v_add_f32_e32 v22, v22, v23
	v_mov_b32_e32 v23, v22
	s_nop 1
	v_permlane16_swap_b32_e32 v22, v23
	v_add_f32_e32 v22, v22, v23
	s_nop 1
	v_add_f32_dpp v22, v22, v22 row_ror:8 row_mask:0xf bank_mask:0xf
	s_nop 1
	v_add_f32_dpp v22, v22, v22 row_ror:4 row_mask:0xf bank_mask:0xf
	s_nop 1
	v_add_f32_dpp v22, v22, v22 quad_perm:[2,3,0,1] row_mask:0xf bank_mask:0xf
	s_nop 1
	v_add_f32_dpp v22, v22, v22 quad_perm:[1,0,3,2] row_mask:0xf bank_mask:0xf
	v_fmamk_f32 v22, v22, 0x3c000000, v170
	v_rsq_f32_e32 v22, v22
	s_nop 0
	v_pk_mul_f32 v[20:21], v[22:23], v[20:21] op_sel_hi:[0,1]
	v_cvt_pk_bf16_f32 v20, v20, v21
	ds_write_b32 v59, v20 offset:272
	s_waitcnt vmcnt(28)
	v_lshlrev_b32_e32 v20, 16, v53
	v_and_b32_e32 v21, 0xffff0000, v53
	ds_bpermute_b32 v53, v28, v20
	ds_bpermute_b32 v23, v28, v21
	s_and_saveexec_b64 s[2:3], s[12:13]
	s_xor_b64 s[18:19], exec, s[2:3]
	s_cbranch_execz .LBB0_248
	s_and_saveexec_b64 s[30:31], s[14:15]
	s_cbranch_execz .LBB0_247
	v_mov_b32_e32 v22, v21
	s_waitcnt lgkmcnt(0)
	v_mul_f32_e32 v20, v212, v20
	v_mul_f32_e32 v21, v214, v22
	v_fmac_f32_e32 v20, v213, v53
	v_fmac_f32_e32 v21, v215, v23

; DI unsigned pk2(float lo, float hi) { f32x2 x = {lo, hi}; return __builtin_bit_cast(unsigned, __builtin_convertvector(x, bf16x2_t)); }
; DI float sum32(float v) { v += __shfl_xor(v, 16); return sum16(v); }
; DI void post_unit(const Params& p, int l, int unit, LAS unsigned char* lds) {
;     ...
;       } else if (s < 7) {
;         rope2<4>(x, hl, cs16 + t * 8); *(unsigned*)pp = pk2(x[0], x[1]);
;       } else if (s == 7) {
;         const float rs = rsqrtf(sum32(x[0] * x[0] + x[1] * x[1]) * (1.0f / 64.0f) + EPS);
;         x *= rs; rope2<4>(x, hl, cs16 + t * 8); if (lane < 32) *(unsigned*)((u16*)(p.ws + WS_KIC) + (tok0 + t) * 64 + 2 * lane) = pk2(x[0], x[1]);
.LBB0_268:
	s_or_b64 exec, exec, s[18:19]
	v_cvt_pk_bf16_f32 v22, v20, v21
	v_add_co_u32_e32 v20, vcc, 0xa002000, v18
	s_nop 1
	v_addc_co_u32_e32 v21, vcc, 0, v19, vcc
	global_store_dword v[20:21], v22, off offset:2048
	s_waitcnt vmcnt(28)
	v_lshlrev_b32_e32 v20, 16, v48
	v_and_b32_e32 v21, 0xffff0000, v48
	s_waitcnt lgkmcnt(0)
	v_mul_f32_e32 v22, v20, v20
	v_fmac_f32_e32 v22, v21, v21
	v_mov_b32_e32 v23, v22
	s_nop 1
	v_permlane16_swap_b32_e32 v22, v23
	v_add_f32_e32 v22, v22, v23
	s_nop 1
	v_add_f32_dpp v22, v22, v22 row_ror:8 row_mask:0xf bank_mask:0xf
	s_nop 1
	v_add_f32_dpp v22, v22, v22 row_ror:4 row_mask:0xf bank_mask:0xf
	s_nop 1
	v_add_f32_dpp v22, v22, v22 quad_perm:[2,3,0,1] row_mask:0xf bank_mask:0xf
	s_nop 1
	v_add_f32_dpp v22, v22, v22 quad_perm:[1,0,3,2] row_mask:0xf bank_mask:0xf
	v_fmamk_f32 v22, v22, 0x3c800000, v170
	v_rsq_f32_e32 v22, v22
	s_nop 0
	v_pk_mul_f32 v[20:21], v[22:23], v[20:21] op_sel_hi:[0,1]
	ds_bpermute_b32 v22, v28, v20
	ds_bpermute_b32 v23, v28, v21
	s_and_saveexec_b64 s[2:3], s[12:13]
	s_xor_b64 s[18:19], exec, s[2:3]
	s_cbranch_execz .LBB0_316
	s_and_saveexec_b64 s[30:31], s[14:15]
	s_cbranch_execz .LBB0_271
	s_waitcnt lgkmcnt(0)
	v_mul_f32_e32 v20, v20, v212
	v_mul_f32_e32 v21, v214, v21
	v_fmac_f32_e32 v20, v213, v22
	v_fmac_f32_e32 v21, v215, v23

; DI unsigned pk2(float lo, float hi) { f32x2 x = {lo, hi}; return __builtin_bit_cast(unsigned, __builtin_convertvector(x, bf16x2_t)); }
; DI float sum16(float v) { v += __shfl_xor(v, 8); v += __shfl_xor(v, 4); v += __shfl_xor(v, 2); v += __shfl_xor(v, 1); return v; }
; DI void post_unit(const Params& p, int l, int unit, LAS unsigned char* lds) {
;     ...
;       } else if (s < 12) {
;         rope2<16>(x, hl, cs64 + t * 32);
;         const int hd = ((s & 1) ? 2 : 0) + hsel;
;         const float lg = log1pf(-exp2f(-5.0f - (float)hd));
;         const float f = (s < 10) ? expf(lg * (float)(t + 1)) : expf(lg * (float)(63 - t)) * 0.125f;
;         x *= f; *(unsigned*)pp = pk2(x[0], x[1]);
;       } else {
;         const float* gn = (s < 14) ? qnc : knc;
;         const float rs = rsqrtf(sum16(x[0] * x[0] + x[1] * x[1]) * (1.0f / 32.0f) + EPS);
;         x[0] *= rs * gn[2 * hl16]; x[1] *= rs * gn[2 * hl16 + 1]; rope2<2>(x, hl16, cs8 + t * 4);
;         if (s < 14) x *= LOG2E * 0.17677669529663687f;
;         *(unsigned*)pp = pk2(x[0], x[1]);
.LBB0_290:
	s_or_b64 exec, exec, s[18:19]
	v_mul_f32_e32 v22, v32, v45
	s_waitcnt lgkmcnt(0)
	v_mul_f32_e32 v23, 0x3fb8aa3b, v22
	v_fma_f32 v44, v22, s64, -v23
	v_rndne_f32_e32 v45, v23
	v_fmac_f32_e32 v44, 0x32a5705f, v22
	v_sub_f32_e32 v23, v23, v45
	v_add_f32_e32 v23, v23, v44
	v_exp_f32_e32 v23, v23
	v_cvt_i32_f32_e32 v44, v45
	v_cmp_ngt_f32_e32 vcc, s65, v22
	v_ldexp_f32 v23, v23, v44
	s_nop 0
	v_cndmask_b32_e32 v23, 0, v23, vcc
	v_cmp_nlt_f32_e32 vcc, s89, v22
	s_nop 1
	v_cndmask_b32_e32 v22, v177, v23, vcc
	v_mul_f32_e32 v22, 0x3e000000, v22
	v_pk_mul_f32 v[20:21], v[22:23], v[20:21] op_sel_hi:[0,1]
	v_cvt_pk_bf16_f32 v22, v20, v21
	v_add_co_u32_e32 v20, vcc, s77, v18
	s_nop 1
	v_addc_co_u32_e32 v21, vcc, 0, v19, vcc
	global_store_dword v[20:21], v22, off offset:3712
	s_waitcnt vmcnt(27)
	v_lshlrev_b32_e32 v20, 16, v43
	v_and_b32_e32 v21, 0xffff0000, v43
	v_mul_f32_e32 v22, v20, v20
	v_fmac_f32_e32 v22, v21, v21
	s_nop 1
	v_add_f32_dpp v22, v22, v22 row_ror:8 row_mask:0xf bank_mask:0xf
	s_nop 1
	v_add_f32_dpp v22, v22, v22 row_ror:4 row_mask:0xf bank_mask:0xf
	s_nop 1
	v_add_f32_dpp v22, v22, v22 quad_perm:[2,3,0,1] row_mask:0xf bank_mask:0xf
	s_nop 1
	v_add_f32_dpp v22, v22, v22 quad_perm:[1,0,3,2] row_mask:0xf bank_mask:0xf
	v_fmamk_f32 v22, v22, 0x3d000000, v170
	v_rsq_f32_e32 v22, v22
	s_nop 0
	v_pk_mul_f32 v[22:23], v[6:7], v[22:23] op_sel_hi:[1,0]
	s_nop 0
	v_pk_mul_f32 v[22:23], v[22:23], v[20:21]
	ds_bpermute_b32 v20, v29, v22
	ds_bpermute_b32 v21, v29, v23
	s_and_saveexec_b64 s[2:3], s[6:7]
	s_xor_b64 s[18:19], exec, s[2:3]
	s_cbranch_execz .LBB0_294
	s_and_saveexec_b64 s[30:31], s[8:9]
	s_cbranch_execz .LBB0_293
	s_waitcnt lgkmcnt(0)
	v_pk_mul_f32 v[48:49], v[22:23], v[228:229]
	v_mul_f32_e32 v22, v229, v20
	v_mov_b32_e32 v20, v23
	v_pk_mul_f32 v[20:21], v[20:21], v[230:231]
	s_nop 0
	v_mov_b32_e32 v49, v20
	v_mov_b32_e32 v23, v21
	v_pk_add_f32 v[22:23], v[48:49], v[22:23]

; DI unsigned pk2(float lo, float hi) { f32x2 x = {lo, hi}; return __builtin_bit_cast(unsigned, __builtin_convertvector(x, bf16x2_t)); }
; DI float sum16(float v) { v += __shfl_xor(v, 8); v += __shfl_xor(v, 4); v += __shfl_xor(v, 2); v += __shfl_xor(v, 1); return v; }
; DI void post_unit(const Params& p, int l, int unit, LAS unsigned char* lds) {
;     ...
;       } else {
;         const float* gn = (s < 14) ? qnc : knc;
;         const float rs = rsqrtf(sum16(x[0] * x[0] + x[1] * x[1]) * (1.0f / 32.0f) + EPS);
;         x[0] *= rs * gn[2 * hl16]; x[1] *= rs * gn[2 * hl16 + 1]; rope2<2>(x, hl16, cs8 + t * 4);
;         if (s < 14) x *= LOG2E * 0.17677669529663687f;
;         *(unsigned*)pp = pk2(x[0], x[1]);
.LBB0_296:
	s_or_b64 exec, exec, s[18:19]
	s_mov_b32 s2, 0x3e8293ee
	s_waitcnt lgkmcnt(0)
	v_pk_mul_f32 v[20:21], v[22:23], s[2:3] op_sel_hi:[1,0]
	s_nop 0
	v_cvt_pk_bf16_f32 v22, v20, v21
	v_add_co_u32_e32 v20, vcc, 0xa003000, v18
	s_nop 1
	v_addc_co_u32_e32 v21, vcc, 0, v19, vcc
	global_store_dword v[20:21], v22, off offset:896
	s_waitcnt vmcnt(27)
	v_lshlrev_b32_e32 v20, 16, v42
	v_and_b32_e32 v21, 0xffff0000, v42
	v_mul_f32_e32 v22, v20, v20
	v_fmac_f32_e32 v22, v21, v21
	s_nop 1
	v_add_f32_dpp v22, v22, v22 row_ror:8 row_mask:0xf bank_mask:0xf
	s_nop 1
	v_add_f32_dpp v22, v22, v22 row_ror:4 row_mask:0xf bank_mask:0xf
	s_nop 1
	v_add_f32_dpp v22, v22, v22 quad_perm:[2,3,0,1] row_mask:0xf bank_mask:0xf
	s_nop 1
	v_add_f32_dpp v22, v22, v22 quad_perm:[1,0,3,2] row_mask:0xf bank_mask:0xf
	v_fmamk_f32 v22, v22, 0x3d000000, v170
	v_rsq_f32_e32 v22, v22
	s_nop 0
	v_pk_mul_f32 v[22:23], v[6:7], v[22:23] op_sel_hi:[1,0]
	s_nop 0
	v_pk_mul_f32 v[22:23], v[22:23], v[20:21]
	ds_bpermute_b32 v20, v29, v22
	ds_bpermute_b32 v21, v29, v23
	s_and_saveexec_b64 s[2:3], s[6:7]
	s_xor_b64 s[18:19], exec, s[2:3]
	s_cbranch_execz .LBB0_300
	s_and_saveexec_b64 s[30:31], s[8:9]
	s_cbranch_execz .LBB0_299
	s_waitcnt lgkmcnt(0)
	v_mul_f32_e32 v22, v22, v228
	v_mul_f32_e32 v23, v23, v230
	v_fmac_f32_e32 v22, v229, v20
	v_fmac_f32_e32 v23, v21, v231

; DI unsigned pk2(float lo, float hi) { f32x2 x = {lo, hi}; return __builtin_bit_cast(unsigned, __builtin_convertvector(x, bf16x2_t)); }
; DI float sum16(float v) { v += __shfl_xor(v, 8); v += __shfl_xor(v, 4); v += __shfl_xor(v, 2); v += __shfl_xor(v, 1); return v; }
; DI void post_unit(const Params& p, int l, int unit, LAS unsigned char* lds) {
;     ...
;       } else {
;         const float* gn = (s < 14) ? qnc : knc;
;         const float rs = rsqrtf(sum16(x[0] * x[0] + x[1] * x[1]) * (1.0f / 32.0f) + EPS);
;         x[0] *= rs * gn[2 * hl16]; x[1] *= rs * gn[2 * hl16 + 1]; rope2<2>(x, hl16, cs8 + t * 4);
;         if (s < 14) x *= LOG2E * 0.17677669529663687f;
;         *(unsigned*)pp = pk2(x[0], x[1]);
.LBB0_302:
	s_or_b64 exec, exec, s[18:19]
	s_mov_b32 s2, 0x3e8293ee
	s_waitcnt lgkmcnt(0)
	v_pk_mul_f32 v[20:21], v[22:23], s[2:3] op_sel_hi:[1,0]
	s_nop 0
	v_cvt_pk_bf16_f32 v22, v20, v21
	v_add_co_u32_e32 v20, vcc, 0xa003000, v18
	s_nop 1
	v_addc_co_u32_e32 v21, vcc, 0, v19, vcc
	global_store_dword v[20:21], v22, off offset:1152
	s_waitcnt vmcnt(27)
	v_lshlrev_b32_e32 v20, 16, v41
	v_and_b32_e32 v21, 0xffff0000, v41
	v_mul_f32_e32 v22, v20, v20
	v_fmac_f32_e32 v22, v21, v21
	s_nop 1
	v_add_f32_dpp v22, v22, v22 row_ror:8 row_mask:0xf bank_mask:0xf
	s_nop 1
	v_add_f32_dpp v22, v22, v22 row_ror:4 row_mask:0xf bank_mask:0xf
	s_nop 1
	v_add_f32_dpp v22, v22, v22 quad_perm:[2,3,0,1] row_mask:0xf bank_mask:0xf
	s_nop 1
	v_add_f32_dpp v22, v22, v22 quad_perm:[1,0,3,2] row_mask:0xf bank_mask:0xf
	v_fmamk_f32 v22, v22, 0x3d000000, v170
	v_rsq_f32_e32 v22, v22
	s_nop 0
	v_pk_mul_f32 v[22:23], v[8:9], v[22:23] op_sel_hi:[1,0]
	s_nop 0
	v_pk_mul_f32 v[22:23], v[22:23], v[20:21]
	ds_bpermute_b32 v20, v29, v22
	ds_bpermute_b32 v21, v29, v23
	s_and_saveexec_b64 s[2:3], s[6:7]
	s_xor_b64 s[18:19], exec, s[2:3]
	s_cbranch_execz .LBB0_306
	s_and_saveexec_b64 s[30:31], s[8:9]
	s_cbranch_execz .LBB0_305
	s_waitcnt lgkmcnt(0)
	v_mul_f32_e32 v22, v22, v228
	v_mul_f32_e32 v23, v23, v230
	v_fmac_f32_e32 v22, v229, v20
	v_fmac_f32_e32 v23, v21, v231
